# P1: modulation GEMM on 48 blocks x 2 units, SSM operand build shared by 208 blocks
# speedup vs baseline: 1.0290x; 1.0035x over previous
; __global__ void __launch_bounds__(512, 2) hybrid_fwd(Params P) {
;     ...
;         if (bid >= 96) {
;         const int gt = (bid - 96) * 512 + tid, NGT = (G - 96) * 512;
;         for (int i = gt; i < DEPTH * 16 * 31 * 256; i += NGT) { const int c = i & 15, cp = (i >> 4) & 15, ti = (i >> 8) % 31, lg = i / (256 * 31); const int tau = ti - 15;
.LBB0_170:
	s_cmp_lt_i32 s78, 2
	s_cselect_b64 s[0:1], -1, 0
	s_cmp_gt_i32 s79, 1
	s_cselect_b64 s[2:3], -1, 0
	s_and_b64 s[0:1], s[0:1], s[2:3]
	s_andn2_b64 vcc, exec, s[0:1]
	s_cbranch_vccnz .LBB0_303
	s_add_i32 s0, 0, 0x20400
	v_readlane_b32 s28, v253, 1
	v_readlane_b32 s29, v253, 0
	v_readlane_b32 s26, v253, 2
	v_mov_b32_e32 v13, s0
	v_mbcnt_lo_u32_b32 v40, -1, 0
	v_mbcnt_hi_u32_b32 v40, -1, v40
	ds_read_b64 v[0:1], v13 offset:280
	v_lshl_add_u32 v144, s26, 6, v40
	s_cmpk_lt_i32 s29, 0x30
	s_waitcnt lgkmcnt(0)
	v_readfirstlane_b32 s7, v1
	v_readfirstlane_b32 s6, v0
	s_cbranch_scc1 .LBB0_209
	s_lshl_b32 s0, s29, 9
	s_add_i32 s0, s0, 0xffffa000
	v_add_u32_e32 v17, s0, v144
	s_lshl_b32 s27, s28, 9
	s_mov_b32 s0, 0x7c000
	s_add_i32 s27, s27, 0xffffa000
	v_cmp_gt_i32_e32 vcc, s0, v17
	v_and_b32_e32 v12, 15, v40
	s_and_saveexec_b64 s[8:9], vcc
	s_cbranch_execz .LBB0_203
	v_mov_b32_e32 v15, 0
	v_lshlrev_b32_e32 v14, 1, v12
	s_mov_b64 s[0:1], 0x1c00000
	s_add_u32 s10, s6, 0x1c00000
	v_lshl_add_u64 v[0:1], s[6:7], 0, v[14:15]
	s_addc_u32 s11, s7, 0
	v_lshlrev_b32_e32 v16, 3, v12
	v_lshl_add_u64 v[18:19], v[0:1], 0, s[0:1]
	s_mov_b64 s[12:13], 0
	s_mov_b32 s30, 0x84210843
	s_mov_b64 s[14:15], 0x400000
	s_mov_b64 s[16:17], 0x200
	s_brev_b32 s31, 8
	s_movk_i32 s33, 0x300
	v_lshlrev_b32_e32 v14, 1, v12
	s_mov_b32 s34, 0x7bfff
	v_mov_b32_e32 v41, 0xf0
	v_mov_b32_e32 v42, v17
	s_branch .LBB0_176

; #define INP(i) ((const float*)ld_ptr(pb, (i)))
;     __device__ bool next(int i, Unit& u) const {
;         const long L = (long)i * G + c; if (c < 0 || L >= tot) return false;
;         if (nsplit > 0 && L >= nwg) { const int r = (int)L - nwg, su = r / nsplit, sp = r % nsplit; u.pm = nMfull + su / nN; u.pn = su % nN; u.z = 0; u.k0 = sp * 256; u.nt = 4; u.split = 1; return true; }
;         const int z = (int)(L / nwg); int wgid = (int)(L % nwg);
;         { const int q = nwg / NXCD, r = nwg % NXCD, xcd = wgid % NXCD, off = wgid / NXCD; wgid = (xcd < r ? xcd * (q + 1) : r * (q + 1) + (xcd - r) * q) + off; }
;         const int nig = WGM * nN, gid = wgid / nig, fm = gid * WGM, gsz = (nM - fm) < WGM ? (nM - fm) : WGM;
;         u.pm = fm + ((wgid % nig) % gsz); u.pn = (wgid % nig) / gsz; u.z = z; u.k0 = 0; u.nt = ntK; u.split = 0; return true;
; __global__ void __launch_bounds__(512, 2) hybrid_fwd(Params P) {
;     ...
;         pg8::Gemm g{SC, WMOD, D, D, D, 0, (size_t)6144 * D * 2}; pg8::Order S; S.init(1, 24, DEPTH, G, bid, D / 64);
;         EpiMod E{MOD, INP(12)};
;         pg8::gemm_phase<EpiMod, true>(ldsl, g, S, E, wave);
.LBB0_209:
	s_barrier
	ds_read_b64 v[0:1], v13 offset:96
	s_cmpk_lt_u32 s29, 0x30
	s_cselect_b64 s[0:1], -1, 0
	s_cmpk_gt_u32 s29, 0x2f
	v_mbcnt_lo_u32_b32 v4, -1, 0
	v_mbcnt_hi_u32_b32 v4, -1, v4
	s_waitcnt lgkmcnt(0)
	v_readfirstlane_b32 s30, v1
	v_readfirstlane_b32 s31, v0
	s_cbranch_scc1 .LBB0_212
	s_and_b32 s2, s29, 0xff
	s_mulk_i32 s2, 0xab
	s_lshr_b32 s51, s2, 12
	s_mul_i32 s2, s51, 24
	s_sub_i32 s2, s29, s2
	s_and_b32 s3, s2, 7
	s_bfe_u32 s2, s2, 0x50003
	s_mul_i32 s3, s3, 3
	s_add_i32 s3, s3, s2
	s_and_b32 s18, s3, 63
	s_andn2_b64 vcc, exec, s[0:1]
	s_cbranch_vccz .LBB0_213

;     __device__ bool next(int i, Unit& u) const {
;         const long L = (long)i * G + c; if (c < 0 || L >= tot) return false;
;         if (nsplit > 0 && L >= nwg) { const int r = (int)L - nwg, su = r / nsplit, sp = r % nsplit; u.pm = nMfull + su / nN; u.pn = su % nN; u.z = 0; u.k0 = sp * 256; u.nt = 4; u.split = 1; return true; }
;         const int z = (int)(L / nwg); int wgid = (int)(L % nwg);
;         { const int q = nwg / NXCD, r = nwg % NXCD, xcd = wgid % NXCD, off = wgid / NXCD; wgid = (xcd < r ? xcd * (q + 1) : r * (q + 1) + (xcd - r) * q) + off; }
;         const int nig = WGM * nN, gid = wgid / nig, fm = gid * WGM, gsz = (nM - fm) < WGM ? (nM - fm) : WGM;
;         u.pm = fm + ((wgid % nig) % gsz); u.pn = (wgid % nig) / gsz; u.z = z; u.k0 = 0; u.nt = ntK; u.split = 0; return true;
.LBB0_218:
	s_add_i32 s40, s40, 1
	s_mul_i32 s0, s40, s46
	s_mul_hi_u32 s1, s40, 48
	s_add_i32 s1, s1, s0
	s_mul_i32 s0, s40, 48
	s_add_u32 s0, s0, s29
	s_addc_u32 s1, s1, 0
	v_cmp_gt_i64_e32 vcc, s[0:1], v[138:139]
	v_cmp_lt_i64_e64 s[2:3], s[0:1], v[136:137]
	s_cbranch_vccnz .LBB0_224
	s_mul_i32 s22, s1, 0xaaaaaaab
	s_mul_hi_u32 s23, s0, 0xaaaaaaab
	s_mul_hi_u32 s19, s1, 0xaaaaaaab
	s_add_u32 s22, s22, s23
	s_mul_i32 s17, s0, 0x2aaaaaaa
	s_addc_u32 s19, s19, 0
	s_mul_hi_u32 s16, s0, 0x2aaaaaaa
	s_add_u32 s17, s17, s22
	s_addc_u32 s16, s16, 0
	s_add_u32 s16, s19, s16
	s_addc_u32 s17, 0, 0
	s_mul_i32 s22, s1, 0x2aaaaaaa
	s_mul_hi_u32 s19, s1, 0x2aaaaaaa
	s_add_u32 s16, s22, s16
	s_addc_u32 s17, s19, s17
	s_ashr_i32 s1, s1, 31
	s_mul_i32 s19, s1, 0x2aaaaaaa
	s_mul_hi_u32 s22, s1, 0xaaaaaaab
	s_add_i32 s19, s22, s19
	s_mul_i32 s1, s1, 0xaaaaaaab
	s_add_i32 s19, s19, s1
	s_add_u32 s16, s16, s1
	s_addc_u32 s17, s17, s19
	s_ashr_i64 s[22:23], s[16:17], 2
	s_lshr_b32 s1, s17, 31
	s_add_u32 s50, s22, s1
	s_mul_i32 s1, s50, 24
	s_sub_i32 s0, s0, s1
	s_bfe_i32 s1, s0, 0x80000
	s_bfe_u32 s1, s1, 0x3000c
	s_add_i32 s16, s0, s1
	s_and_b32 s1, s16, 0xf8
	s_sub_i32 s0, s0, s1
	s_bfe_i32 s19, s0, 0x80000
	s_sext_i32_i16 s0, s19
	s_cmp_gt_i32 s0, -1
	s_mov_b64 s[0:1], -1
	s_cbranch_scc0 .LBB0_221
	s_mul_i32 s17, s19, 3
	s_mov_b64 s[0:1], 0
